# u8 + pooled up-GEMM tiles handed out group by group (32 consecutive tickets = one 4x8 tile block) for L2 locality
# speedup vs baseline: 1.0044x; 1.0044x over previous
;     __host__ __device__ bool next(int i, Unit& u) const {
;     ...
;         int wgid = (int)L; { const int q = nwg / NXCD, r = nwg % NXCD, xcd = wgid % NXCD, off = wgid / NXCD; wgid = (xcd < r ? xcd * (q + 1) : r * (q + 1) + (xcd - r) * q) + off; }
;         const int nig = wgm * nN, gid = wgid / nig, fm = gid * wgm, gsz = (nM - fm) < wgm ? (nM - fm) : wgm;
;         u.pm = fm + ((wgid % nig) % gsz); u.pn = (wgid % nig) / gsz; if (rev) u.pm = nM - 1 - u.pm; return true;
.Ldq_m2:
	s_sub_u32 s100, s101, s14
	s_cmp_eq_u32 s100, 512
	s_cbranch_scc0 .Ldq_m3
	s_cmp_lt_u32 s99, 512
	s_cbranch_scc0 .Ldq_m3
	s_and_b32 s100, s99, 63
	s_lshl_b32 s100, s100, 3
	s_lshr_b32 s99, s99, 6
	s_add_u32 s99, s99, s100
